# NORM GEMM loops now run all 16 K-steps (clamped last prefetch); compiler's peeled last K-step + shuffle reduction replaced by a DPP row reduction of the sum-of-squares
# speedup vs baseline: 1.0110x; 1.0110x over previous
.LBB0_104:
	s_waitcnt lgkmcnt(0)
	s_barrier
	s_min_u32 s98, s2, 0x380
	s_waitcnt vmcnt(11)
	ds_write_b128 v243, v[160:163] offset:36864
	v_add_u32_e32 v188, s98, v200
	v_add_u32_e32 v188, 0x40, v188
	v_lshl_add_u64 v[160:161], v[188:189], 1, s[24:25]
	global_load_dwordx4 v[160:163], v[160:161], off
	s_waitcnt vmcnt(11)
	ds_write_b128 v243, v[164:167] offset:41472
	v_add_u32_e32 v188, s98, v200
	v_add_u32_e32 v188, 0x8040, v188
	v_lshl_add_u64 v[164:165], v[188:189], 1, s[24:25]
	global_load_dwordx4 v[164:167], v[164:165], off
	s_waitcnt vmcnt(11)
	ds_write_b128 v243, v[168:171] offset:46080
	v_add_u32_e32 v188, s98, v200
	v_add_u32_e32 v188, 0x10040, v188
	v_lshl_add_u64 v[168:169], v[188:189], 1, s[24:25]
	global_load_dwordx4 v[168:171], v[168:169], off
	s_waitcnt vmcnt(11)
	ds_write_b128 v243, v[172:175] offset:50688
	v_add_u32_e32 v188, s98, v200
	v_add_u32_e32 v188, 0x18040, v188
	v_lshl_add_u64 v[172:173], v[188:189], 1, s[24:25]
	global_load_dwordx4 v[172:175], v[172:173], off
	s_waitcnt vmcnt(11)
	ds_write_b128 v243, v[156:159]
	v_dot2c_f32_bf16_e32 v197, v156, v156
	v_dot2c_f32_bf16_e32 v197, v157, v157
	v_dot2c_f32_bf16_e32 v197, v158, v158
	v_dot2c_f32_bf16_e32 v197, v159, v159
	v_add_u32_e32 v188, s98, v198
	v_add_u32_e32 v188, 0x40, v188
	v_lshl_add_u64 v[156:157], v[188:189], 1, s[36:37]
	global_load_dwordx4 v[156:159], v[156:157], off
	s_waitcnt vmcnt(11)
	ds_write_b128 v243, v[152:155] offset:4608
	v_dot2c_f32_bf16_e32 v196, v152, v152
	v_dot2c_f32_bf16_e32 v196, v153, v153
	v_dot2c_f32_bf16_e32 v196, v154, v154
	v_dot2c_f32_bf16_e32 v196, v155, v155
	v_add_u32_e32 v188, s98, v198
	v_add_u32_e32 v188, 0x8040, v188
	v_lshl_add_u64 v[152:153], v[188:189], 1, s[36:37]
	global_load_dwordx4 v[152:155], v[152:153], off
	s_waitcnt vmcnt(11)
	ds_write_b128 v243, v[148:151] offset:9216
	v_dot2c_f32_bf16_e32 v195, v148, v148
	v_dot2c_f32_bf16_e32 v195, v149, v149
	v_dot2c_f32_bf16_e32 v195, v150, v150
	v_dot2c_f32_bf16_e32 v195, v151, v151
	v_add_u32_e32 v188, s98, v198
	v_add_u32_e32 v188, 0x10040, v188
	v_lshl_add_u64 v[148:149], v[188:189], 1, s[36:37]
	global_load_dwordx4 v[148:151], v[148:149], off
	s_waitcnt vmcnt(11)
	ds_write_b128 v243, v[144:147] offset:13824
	v_dot2c_f32_bf16_e32 v194, v144, v144
	v_dot2c_f32_bf16_e32 v194, v145, v145
	v_dot2c_f32_bf16_e32 v194, v146, v146
	v_dot2c_f32_bf16_e32 v194, v147, v147
	v_add_u32_e32 v188, s98, v198
	v_add_u32_e32 v188, 0x18040, v188
	v_lshl_add_u64 v[144:145], v[188:189], 1, s[36:37]
	global_load_dwordx4 v[144:147], v[144:145], off
	s_waitcnt vmcnt(11)
	ds_write_b128 v243, v[140:143] offset:18432
	v_dot2c_f32_bf16_e32 v193, v140, v140
	v_dot2c_f32_bf16_e32 v193, v141, v141
	v_dot2c_f32_bf16_e32 v193, v142, v142
	v_dot2c_f32_bf16_e32 v193, v143, v143
	v_add_u32_e32 v188, s98, v198
	v_add_u32_e32 v188, 0x20040, v188
	v_lshl_add_u64 v[140:141], v[188:189], 1, s[36:37]
	global_load_dwordx4 v[140:143], v[140:141], off
	s_waitcnt vmcnt(11)
	ds_write_b128 v243, v[136:139] offset:23040
	v_dot2c_f32_bf16_e32 v192, v136, v136
	v_dot2c_f32_bf16_e32 v192, v137, v137
	v_dot2c_f32_bf16_e32 v192, v138, v138
	v_dot2c_f32_bf16_e32 v192, v139, v139
	v_add_u32_e32 v188, s98, v198
	v_add_u32_e32 v188, 0x28040, v188
	v_lshl_add_u64 v[136:137], v[188:189], 1, s[36:37]
	global_load_dwordx4 v[136:139], v[136:137], off
	s_waitcnt vmcnt(11)
	ds_write_b128 v243, v[132:135] offset:27648
	v_dot2c_f32_bf16_e32 v191, v132, v132
	v_dot2c_f32_bf16_e32 v191, v133, v133
	v_dot2c_f32_bf16_e32 v191, v134, v134
	v_dot2c_f32_bf16_e32 v191, v135, v135
	v_add_u32_e32 v188, s98, v198
	v_add_u32_e32 v188, 0x30040, v188
	v_lshl_add_u64 v[132:133], v[188:189], 1, s[36:37]
	global_load_dwordx4 v[132:135], v[132:133], off
	s_waitcnt vmcnt(11)
	ds_write_b128 v243, v[128:131] offset:32256
	v_dot2c_f32_bf16_e32 v190, v128, v128
	v_dot2c_f32_bf16_e32 v190, v129, v129
	v_dot2c_f32_bf16_e32 v190, v130, v130
	v_dot2c_f32_bf16_e32 v190, v131, v131
	v_add_u32_e32 v188, s98, v198
	v_add_u32_e32 v188, 0x38040, v188
	v_lshl_add_u64 v[128:129], v[188:189], 1, s[36:37]
	global_load_dwordx4 v[128:131], v[128:129], off
	s_waitcnt lgkmcnt(0)
	s_barrier
; template <bool NORM, bool DEEP, int MTW, int KSEG, class HOOK>
; DI void gemm_core_h(const bfu* __restrict__ A, int lda, const bfu* __restrict__ Bt, int ldb, int K, int m0, int n0,
;                     f32x16 (&acc)[MTW][2], char* smem, HOOK hook) {
;     ...
;   if (DEEP) {
;     for (int kt = 0; kt < nk; kt += 2) {
;       GEMM_STEP(ra0, rb0, kt, 2)
;       GEMM_STEP(ra1, rb1, kt + 1, 2)
;     }
;   } else {
;     for (int kt = 0; kt < nk; ++kt) {
;       GEMM_STEP(ra0, rb0, kt, 1)
;       if (KSEG > 0) { if (((kt + 1) % (KSEG > 0 ? KSEG : 1)) == 0) hook((kt + 1) / (KSEG > 0 ? KSEG : 1) - 1); }
;     }
;   }
;     ...
;   if (NORM) {
; #pragma unroll
;     for (int j = 0; j < NA; ++j) {
;       float v = ssq[j];
;       v += __shfl_xor(v, 1); v += __shfl_xor(v, 2); v += __shfl_xor(v, 4);
;       if (lkc == 0) rstd_s[lrow + 32 * j] = rsqrtf(v / (float)K + EPS);
;     }
	ds_read_b128 v[244:247], v242 offset:36864
	ds_read_b128 v[184:187], v242 offset:41472
	ds_read_b128 v[248:251], v201
	ds_read_b128 v[232:235], v201 offset:4608
	s_waitcnt lgkmcnt(1)
	v_mfma_f32_32x32x16_bf16 v[112:127], v[248:251], v[244:247], v[112:127]
	v_mfma_f32_32x32x16_bf16 v[96:111], v[248:251], v[184:187], v[96:111]
	ds_read_b128 v[248:251], v201 offset:9216
	s_waitcnt lgkmcnt(1)
	v_mfma_f32_32x32x16_bf16 v[80:95], v[232:235], v[244:247], v[80:95]
	v_mfma_f32_32x32x16_bf16 v[64:79], v[232:235], v[184:187], v[64:79]
	ds_read_b128 v[232:235], v199
	ds_read_b128 v[176:179], v242 offset:36896
	ds_read_b128 v[180:183], v242 offset:41504
	s_waitcnt lgkmcnt(3)
	v_mfma_f32_32x32x16_bf16 v[48:63], v[248:251], v[244:247], v[48:63]
	v_mfma_f32_32x32x16_bf16 v[32:47], v[248:251], v[184:187], v[32:47]
	ds_read_b128 v[248:251], v201 offset:32
	s_waitcnt lgkmcnt(3)
	v_mfma_f32_32x32x16_bf16 v[16:31], v[232:235], v[244:247], v[16:31]
	v_mfma_f32_32x32x16_bf16 v[0:15], v[232:235], v[184:187], v[0:15]
	ds_read_b128 v[232:235], v201 offset:4640
	s_waitcnt lgkmcnt(1)
	v_mfma_f32_32x32x16_bf16 v[112:127], v[248:251], v[176:179], v[112:127]
	v_mfma_f32_32x32x16_bf16 v[96:111], v[248:251], v[180:183], v[96:111]
	ds_read_b128 v[248:251], v201 offset:9248
	s_waitcnt lgkmcnt(1)
	v_mfma_f32_32x32x16_bf16 v[80:95], v[232:235], v[176:179], v[80:95]
	v_mfma_f32_32x32x16_bf16 v[64:79], v[232:235], v[180:183], v[64:79]
	ds_read_b128 v[232:235], v199 offset:32
	ds_read_b128 v[244:247], v242 offset:36928
	ds_read_b128 v[184:187], v242 offset:41536
	s_waitcnt lgkmcnt(3)
	v_mfma_f32_32x32x16_bf16 v[48:63], v[248:251], v[176:179], v[48:63]
	v_mfma_f32_32x32x16_bf16 v[32:47], v[248:251], v[180:183], v[32:47]
	ds_read_b128 v[248:251], v201 offset:64
	s_waitcnt lgkmcnt(3)
	v_mfma_f32_32x32x16_bf16 v[16:31], v[232:235], v[176:179], v[16:31]
	v_mfma_f32_32x32x16_bf16 v[0:15], v[232:235], v[180:183], v[0:15]
	ds_read_b128 v[232:235], v201 offset:4672
	s_waitcnt lgkmcnt(1)
	v_mfma_f32_32x32x16_bf16 v[112:127], v[248:251], v[244:247], v[112:127]
	v_mfma_f32_32x32x16_bf16 v[96:111], v[248:251], v[184:187], v[96:111]
	ds_read_b128 v[248:251], v201 offset:9280
	s_waitcnt lgkmcnt(1)
	v_mfma_f32_32x32x16_bf16 v[80:95], v[232:235], v[244:247], v[80:95]
	v_mfma_f32_32x32x16_bf16 v[64:79], v[232:235], v[184:187], v[64:79]
	ds_read_b128 v[232:235], v199 offset:64
	ds_read_b128 v[176:179], v242 offset:36960
	ds_read_b128 v[180:183], v242 offset:41568
	s_waitcnt lgkmcnt(3)
	v_mfma_f32_32x32x16_bf16 v[48:63], v[248:251], v[244:247], v[48:63]
	v_mfma_f32_32x32x16_bf16 v[32:47], v[248:251], v[184:187], v[32:47]
	ds_read_b128 v[248:251], v201 offset:96
	s_waitcnt lgkmcnt(3)
	v_mfma_f32_32x32x16_bf16 v[16:31], v[232:235], v[244:247], v[16:31]
	v_mfma_f32_32x32x16_bf16 v[0:15], v[232:235], v[184:187], v[0:15]
	ds_read_b128 v[232:235], v201 offset:4704
	s_waitcnt lgkmcnt(1)
	v_mfma_f32_32x32x16_bf16 v[112:127], v[248:251], v[176:179], v[112:127]
	v_mfma_f32_32x32x16_bf16 v[96:111], v[248:251], v[180:183], v[96:111]
	ds_read_b128 v[248:251], v201 offset:9312
	s_waitcnt lgkmcnt(1)
	v_mfma_f32_32x32x16_bf16 v[80:95], v[232:235], v[176:179], v[80:95]
	v_mfma_f32_32x32x16_bf16 v[64:79], v[232:235], v[180:183], v[64:79]
	ds_read_b128 v[232:235], v199 offset:96
	s_waitcnt lgkmcnt(1)
	v_mfma_f32_32x32x16_bf16 v[48:63], v[248:251], v[176:179], v[48:63]
	v_mfma_f32_32x32x16_bf16 v[32:47], v[248:251], v[180:183], v[32:47]
	s_waitcnt lgkmcnt(0)
	v_mfma_f32_32x32x16_bf16 v[16:31], v[232:235], v[176:179], v[16:31]
	v_mfma_f32_32x32x16_bf16 v[0:15], v[232:235], v[180:183], v[0:15]
	s_add_i32 s2, s2, 64
	s_cmpk_eq_i32 s2, 0x400
	s_cbranch_scc0 .LBB0_104
	s_waitcnt vmcnt(0)
	v_mbcnt_hi_u32_b32 v156, -1, v226
	v_xor_b32_e32 v156, 1, v156
	v_lshlrev_b32_e32 v156, 2, v156
	v_add_f32_dpp v197, v197, v197 quad_perm:[1,0,3,2] row_mask:0xf bank_mask:0xf
	v_add_f32_dpp v196, v196, v196 quad_perm:[1,0,3,2] row_mask:0xf bank_mask:0xf
	v_add_f32_dpp v195, v195, v195 quad_perm:[1,0,3,2] row_mask:0xf bank_mask:0xf
	v_add_f32_dpp v194, v194, v194 quad_perm:[1,0,3,2] row_mask:0xf bank_mask:0xf
	v_add_f32_dpp v193, v193, v193 quad_perm:[1,0,3,2] row_mask:0xf bank_mask:0xf
	v_add_f32_dpp v192, v192, v192 quad_perm:[1,0,3,2] row_mask:0xf bank_mask:0xf
	v_add_f32_dpp v191, v191, v191 quad_perm:[1,0,3,2] row_mask:0xf bank_mask:0xf
	v_add_f32_dpp v190, v190, v190 quad_perm:[1,0,3,2] row_mask:0xf bank_mask:0xf
	v_add_f32_dpp v197, v197, v197 quad_perm:[2,3,0,1] row_mask:0xf bank_mask:0xf
	v_add_f32_dpp v196, v196, v196 quad_perm:[2,3,0,1] row_mask:0xf bank_mask:0xf
	v_add_f32_dpp v195, v195, v195 quad_perm:[2,3,0,1] row_mask:0xf bank_mask:0xf
	v_add_f32_dpp v194, v194, v194 quad_perm:[2,3,0,1] row_mask:0xf bank_mask:0xf
	v_add_f32_dpp v193, v193, v193 quad_perm:[2,3,0,1] row_mask:0xf bank_mask:0xf
	v_add_f32_dpp v192, v192, v192 quad_perm:[2,3,0,1] row_mask:0xf bank_mask:0xf
	v_add_f32_dpp v191, v191, v191 quad_perm:[2,3,0,1] row_mask:0xf bank_mask:0xf
	v_add_f32_dpp v190, v190, v190 quad_perm:[2,3,0,1] row_mask:0xf bank_mask:0xf
	v_add_f32_dpp v197, v197, v197 row_half_mirror row_mask:0xf bank_mask:0xf
	v_add_f32_dpp v196, v196, v196 row_half_mirror row_mask:0xf bank_mask:0xf
	v_add_f32_dpp v195, v195, v195 row_half_mirror row_mask:0xf bank_mask:0xf
	v_add_f32_dpp v194, v194, v194 row_half_mirror row_mask:0xf bank_mask:0xf
	v_add_f32_dpp v193, v193, v193 row_half_mirror row_mask:0xf bank_mask:0xf
	v_add_f32_dpp v192, v192, v192 row_half_mirror row_mask:0xf bank_mask:0xf
	v_add_f32_dpp v191, v191, v191 row_half_mirror row_mask:0xf bank_mask:0xf
	v_add_f32_dpp v190, v190, v190 row_half_mirror row_mask:0xf bank_mask:0xf
	v_lshlrev_b32_e32 v136, 2, v240
	v_cmp_eq_u32_e64 s[2:3], 0, v241
	v_fmamk_f32 v128, v197, 0x3a800000, v225
	v_fmamk_f32 v129, v196, 0x3a800000, v225
	v_fmamk_f32 v130, v195, 0x3a800000, v225
	v_fmamk_f32 v131, v194, 0x3a800000, v225
	v_fmamk_f32 v132, v193, 0x3a800000, v225
	v_fmamk_f32 v133, v192, 0x3a800000, v225
	v_fmamk_f32 v134, v191, 0x3a800000, v225
	v_fmamk_f32 v135, v190, 0x3a800000, v225
	v_rsq_f32_e32 v128, v128
	v_rsq_f32_e32 v129, v129
	v_rsq_f32_e32 v130, v130
	v_rsq_f32_e32 v131, v131
	v_rsq_f32_e32 v132, v132
	v_rsq_f32_e32 v133, v133
	v_rsq_f32_e32 v134, v134
	v_rsq_f32_e32 v135, v135
	s_and_saveexec_b64 s[4:5], s[2:3]
	ds_write_b32 v136, v128 offset:55296
	ds_write_b32 v136, v129 offset:55424
	ds_write_b32 v136, v130 offset:55552
	ds_write_b32 v136, v131 offset:55680
	ds_write_b32 v136, v132 offset:55808
	ds_write_b32 v136, v133 offset:55936
	ds_write_b32 v136, v134 offset:56064
	ds_write_b32 v136, v135 offset:56192
	s_branch .LBB0_102

.LBB0_782:
	s_waitcnt lgkmcnt(0)
	s_barrier
	v_readlane_b32 s52, v253, 32
	v_readlane_b32 s66, v253, 46
	v_readlane_b32 s67, v253, 47
	v_readlane_b32 s53, v253, 33
	v_readlane_b32 s54, v253, 34
	v_readlane_b32 s55, v253, 35
	v_readlane_b32 s56, v253, 36
	v_readlane_b32 s57, v253, 37
	v_readlane_b32 s58, v253, 38
	v_readlane_b32 s59, v253, 39
	v_readlane_b32 s60, v253, 40
	v_readlane_b32 s61, v253, 41
	v_readlane_b32 s62, v253, 42
	v_readlane_b32 s63, v253, 43
	v_readlane_b32 s64, v253, 44
	v_readlane_b32 s65, v253, 45
	s_min_u32 s98, s2, 0x380
	s_waitcnt vmcnt(11)
	ds_write_b128 v212, v[160:163] offset:36864
	v_add_u32_e32 v188, s98, v204
	v_add_u32_e32 v188, 0x40, v188
	v_lshl_add_u64 v[160:161], v[188:189], 1, s[66:67]
	global_load_dwordx4 v[160:163], v[160:161], off
	s_waitcnt vmcnt(11)
	ds_write_b128 v212, v[164:167] offset:41472
	v_add_u32_e32 v188, s98, v204
	v_add_u32_e32 v188, 0x8040, v188
	v_lshl_add_u64 v[164:165], v[188:189], 1, s[66:67]
	global_load_dwordx4 v[164:167], v[164:165], off
	s_waitcnt vmcnt(11)
	ds_write_b128 v212, v[168:171] offset:46080
	v_add_u32_e32 v188, s98, v204
	v_add_u32_e32 v188, 0x10040, v188
	v_lshl_add_u64 v[168:169], v[188:189], 1, s[66:67]
	global_load_dwordx4 v[168:171], v[168:169], off
	s_waitcnt vmcnt(11)
	ds_write_b128 v212, v[172:175] offset:50688
	v_add_u32_e32 v188, s98, v204
	v_add_u32_e32 v188, 0x18040, v188
	v_lshl_add_u64 v[172:173], v[188:189], 1, s[66:67]
	global_load_dwordx4 v[172:175], v[172:173], off
	s_waitcnt vmcnt(11)
	ds_write_b128 v212, v[156:159]
	v_dot2c_f32_bf16_e32 v201, v156, v156
	v_dot2c_f32_bf16_e32 v201, v157, v157
	v_dot2c_f32_bf16_e32 v201, v158, v158
	v_dot2c_f32_bf16_e32 v201, v159, v159
	v_add_u32_e32 v188, s98, v202
	v_add_u32_e32 v188, 0x40, v188
	v_lshl_add_u64 v[156:157], v[188:189], 1, s[38:39]
	global_load_dwordx4 v[156:159], v[156:157], off
	s_waitcnt vmcnt(11)
	ds_write_b128 v212, v[152:155] offset:4608
	v_dot2c_f32_bf16_e32 v200, v152, v152
	v_dot2c_f32_bf16_e32 v200, v153, v153
	v_dot2c_f32_bf16_e32 v200, v154, v154
	v_dot2c_f32_bf16_e32 v200, v155, v155
	v_add_u32_e32 v188, s98, v202
	v_add_u32_e32 v188, 0x8040, v188
	v_lshl_add_u64 v[152:153], v[188:189], 1, s[38:39]
	global_load_dwordx4 v[152:155], v[152:153], off
	s_waitcnt vmcnt(11)
	ds_write_b128 v212, v[148:151] offset:9216
	v_dot2c_f32_bf16_e32 v199, v148, v148
	v_dot2c_f32_bf16_e32 v199, v149, v149
	v_dot2c_f32_bf16_e32 v199, v150, v150
	v_dot2c_f32_bf16_e32 v199, v151, v151
	v_add_u32_e32 v188, s98, v202
	v_add_u32_e32 v188, 0x10040, v188
	v_lshl_add_u64 v[148:149], v[188:189], 1, s[38:39]
	global_load_dwordx4 v[148:151], v[148:149], off
	s_waitcnt vmcnt(11)
	ds_write_b128 v212, v[144:147] offset:13824
	v_dot2c_f32_bf16_e32 v198, v144, v144
	v_dot2c_f32_bf16_e32 v198, v145, v145
	v_dot2c_f32_bf16_e32 v198, v146, v146
	v_dot2c_f32_bf16_e32 v198, v147, v147
	v_add_u32_e32 v188, s98, v202
	v_add_u32_e32 v188, 0x18040, v188
	v_lshl_add_u64 v[144:145], v[188:189], 1, s[38:39]
	global_load_dwordx4 v[144:147], v[144:145], off
	s_waitcnt vmcnt(11)
	ds_write_b128 v212, v[140:143] offset:18432
	v_dot2c_f32_bf16_e32 v197, v140, v140
	v_dot2c_f32_bf16_e32 v197, v141, v141
	v_dot2c_f32_bf16_e32 v197, v142, v142
	v_dot2c_f32_bf16_e32 v197, v143, v143
	v_add_u32_e32 v188, s98, v202
	v_add_u32_e32 v188, 0x20040, v188
	v_lshl_add_u64 v[140:141], v[188:189], 1, s[38:39]
	global_load_dwordx4 v[140:143], v[140:141], off
	s_waitcnt vmcnt(11)
	ds_write_b128 v212, v[136:139] offset:23040
	v_dot2c_f32_bf16_e32 v196, v136, v136
	v_dot2c_f32_bf16_e32 v196, v137, v137
	v_dot2c_f32_bf16_e32 v196, v138, v138
	v_dot2c_f32_bf16_e32 v196, v139, v139
	v_add_u32_e32 v188, s98, v202
	v_add_u32_e32 v188, 0x28040, v188
	v_lshl_add_u64 v[136:137], v[188:189], 1, s[38:39]
	global_load_dwordx4 v[136:139], v[136:137], off
	s_waitcnt vmcnt(11)
	ds_write_b128 v212, v[132:135] offset:27648
	v_dot2c_f32_bf16_e32 v195, v132, v132
	v_dot2c_f32_bf16_e32 v195, v133, v133
	v_dot2c_f32_bf16_e32 v195, v134, v134
	v_dot2c_f32_bf16_e32 v195, v135, v135
	v_add_u32_e32 v188, s98, v202
	v_add_u32_e32 v188, 0x30040, v188
	v_lshl_add_u64 v[132:133], v[188:189], 1, s[38:39]
	global_load_dwordx4 v[132:135], v[132:133], off
	s_waitcnt vmcnt(11)
	ds_write_b128 v212, v[128:131] offset:32256
	v_dot2c_f32_bf16_e32 v194, v128, v128
	v_dot2c_f32_bf16_e32 v194, v129, v129
	v_dot2c_f32_bf16_e32 v194, v130, v130
	v_dot2c_f32_bf16_e32 v194, v131, v131
	v_add_u32_e32 v188, s98, v202
	v_add_u32_e32 v188, 0x38040, v188
	v_lshl_add_u64 v[128:129], v[188:189], 1, s[38:39]
	global_load_dwordx4 v[128:131], v[128:129], off
	s_waitcnt lgkmcnt(0)
	s_barrier
; template <bool NORM, bool DEEP, int MTW, int KSEG, class HOOK>
; DI void gemm_core_h(const bfu* __restrict__ A, int lda, const bfu* __restrict__ Bt, int ldb, int K, int m0, int n0,
;                     f32x16 (&acc)[MTW][2], char* smem, HOOK hook) {
;     ...
;   if (DEEP) {
;     for (int kt = 0; kt < nk; kt += 2) {
;       GEMM_STEP(ra0, rb0, kt, 2)
;       GEMM_STEP(ra1, rb1, kt + 1, 2)
;     }
;   } else {
;     for (int kt = 0; kt < nk; ++kt) {
;       GEMM_STEP(ra0, rb0, kt, 1)
;       if (KSEG > 0) { if (((kt + 1) % (KSEG > 0 ? KSEG : 1)) == 0) hook((kt + 1) / (KSEG > 0 ? KSEG : 1) - 1); }
;     }
;   }
;     ...
;   if (NORM) {
; #pragma unroll
;     for (int j = 0; j < NA; ++j) {
;       float v = ssq[j];
;       v += __shfl_xor(v, 1); v += __shfl_xor(v, 2); v += __shfl_xor(v, 4);
;       if (lkc == 0) rstd_s[lrow + 32 * j] = rsqrtf(v / (float)K + EPS);
;     }
	ds_read_b128 v[214:217], v211 offset:36864
	ds_read_b128 v[184:187], v211 offset:41472
	ds_read_b128 v[218:221], v205
	ds_read_b128 v[238:241], v205 offset:4608
	s_waitcnt lgkmcnt(1)
	v_mfma_f32_32x32x16_bf16 v[112:127], v[218:221], v[214:217], v[112:127]
	v_mfma_f32_32x32x16_bf16 v[96:111], v[218:221], v[184:187], v[96:111]
	ds_read_b128 v[218:221], v205 offset:9216
	s_waitcnt lgkmcnt(1)
	v_mfma_f32_32x32x16_bf16 v[80:95], v[238:241], v[214:217], v[80:95]
	v_mfma_f32_32x32x16_bf16 v[64:79], v[238:241], v[184:187], v[64:79]
	ds_read_b128 v[238:241], v203
	ds_read_b128 v[176:179], v211 offset:36896
	ds_read_b128 v[180:183], v211 offset:41504
	s_waitcnt lgkmcnt(3)
	v_mfma_f32_32x32x16_bf16 v[48:63], v[218:221], v[214:217], v[48:63]
	v_mfma_f32_32x32x16_bf16 v[32:47], v[218:221], v[184:187], v[32:47]
	ds_read_b128 v[218:221], v205 offset:32
	s_waitcnt lgkmcnt(3)
	v_mfma_f32_32x32x16_bf16 v[16:31], v[238:241], v[214:217], v[16:31]
	v_mfma_f32_32x32x16_bf16 v[0:15], v[238:241], v[184:187], v[0:15]
	ds_read_b128 v[238:241], v205 offset:4640
	s_waitcnt lgkmcnt(1)
	v_mfma_f32_32x32x16_bf16 v[112:127], v[218:221], v[176:179], v[112:127]
	v_mfma_f32_32x32x16_bf16 v[96:111], v[218:221], v[180:183], v[96:111]
	ds_read_b128 v[218:221], v205 offset:9248
	s_waitcnt lgkmcnt(1)
	v_mfma_f32_32x32x16_bf16 v[80:95], v[238:241], v[176:179], v[80:95]
	v_mfma_f32_32x32x16_bf16 v[64:79], v[238:241], v[180:183], v[64:79]
	ds_read_b128 v[238:241], v203 offset:32
	ds_read_b128 v[214:217], v211 offset:36928
	ds_read_b128 v[184:187], v211 offset:41536
	s_waitcnt lgkmcnt(3)
	v_mfma_f32_32x32x16_bf16 v[48:63], v[218:221], v[176:179], v[48:63]
	v_mfma_f32_32x32x16_bf16 v[32:47], v[218:221], v[180:183], v[32:47]
	ds_read_b128 v[218:221], v205 offset:64
	s_waitcnt lgkmcnt(3)
	v_mfma_f32_32x32x16_bf16 v[16:31], v[238:241], v[176:179], v[16:31]
	v_mfma_f32_32x32x16_bf16 v[0:15], v[238:241], v[180:183], v[0:15]
	ds_read_b128 v[238:241], v205 offset:4672
	s_waitcnt lgkmcnt(1)
	v_mfma_f32_32x32x16_bf16 v[112:127], v[218:221], v[214:217], v[112:127]
	v_mfma_f32_32x32x16_bf16 v[96:111], v[218:221], v[184:187], v[96:111]
	ds_read_b128 v[218:221], v205 offset:9280
	s_waitcnt lgkmcnt(1)
	v_mfma_f32_32x32x16_bf16 v[80:95], v[238:241], v[214:217], v[80:95]
	v_mfma_f32_32x32x16_bf16 v[64:79], v[238:241], v[184:187], v[64:79]
	ds_read_b128 v[238:241], v203 offset:64
	ds_read_b128 v[176:179], v211 offset:36960
	ds_read_b128 v[180:183], v211 offset:41568
	s_waitcnt lgkmcnt(3)
	v_mfma_f32_32x32x16_bf16 v[48:63], v[218:221], v[214:217], v[48:63]
	v_mfma_f32_32x32x16_bf16 v[32:47], v[218:221], v[184:187], v[32:47]
	ds_read_b128 v[218:221], v205 offset:96
	s_waitcnt lgkmcnt(3)
	v_mfma_f32_32x32x16_bf16 v[16:31], v[238:241], v[214:217], v[16:31]
	v_mfma_f32_32x32x16_bf16 v[0:15], v[238:241], v[184:187], v[0:15]
	ds_read_b128 v[238:241], v205 offset:4704
	s_waitcnt lgkmcnt(1)
	v_mfma_f32_32x32x16_bf16 v[112:127], v[218:221], v[176:179], v[112:127]
	v_mfma_f32_32x32x16_bf16 v[96:111], v[218:221], v[180:183], v[96:111]
	ds_read_b128 v[218:221], v205 offset:9312
	s_waitcnt lgkmcnt(1)
	v_mfma_f32_32x32x16_bf16 v[80:95], v[238:241], v[176:179], v[80:95]
	v_mfma_f32_32x32x16_bf16 v[64:79], v[238:241], v[180:183], v[64:79]
	ds_read_b128 v[238:241], v203 offset:96
	s_waitcnt lgkmcnt(1)
	v_mfma_f32_32x32x16_bf16 v[48:63], v[218:221], v[176:179], v[48:63]
	v_mfma_f32_32x32x16_bf16 v[32:47], v[218:221], v[180:183], v[32:47]
	s_waitcnt lgkmcnt(0)
	v_mfma_f32_32x32x16_bf16 v[16:31], v[238:241], v[176:179], v[16:31]
	v_mfma_f32_32x32x16_bf16 v[0:15], v[238:241], v[180:183], v[0:15]
	s_add_i32 s2, s2, 64
	s_cmpk_eq_i32 s2, 0x400
	s_cbranch_scc0 .LBB0_782
	s_waitcnt vmcnt(0)
	v_add_f32_dpp v201, v201, v201 quad_perm:[1,0,3,2] row_mask:0xf bank_mask:0xf
	v_add_f32_dpp v200, v200, v200 quad_perm:[1,0,3,2] row_mask:0xf bank_mask:0xf
	v_add_f32_dpp v199, v199, v199 quad_perm:[1,0,3,2] row_mask:0xf bank_mask:0xf
	v_add_f32_dpp v198, v198, v198 quad_perm:[1,0,3,2] row_mask:0xf bank_mask:0xf
	v_add_f32_dpp v197, v197, v197 quad_perm:[1,0,3,2] row_mask:0xf bank_mask:0xf
	v_add_f32_dpp v196, v196, v196 quad_perm:[1,0,3,2] row_mask:0xf bank_mask:0xf
	v_add_f32_dpp v195, v195, v195 quad_perm:[1,0,3,2] row_mask:0xf bank_mask:0xf
	v_add_f32_dpp v194, v194, v194 quad_perm:[1,0,3,2] row_mask:0xf bank_mask:0xf
	v_add_f32_dpp v201, v201, v201 quad_perm:[2,3,0,1] row_mask:0xf bank_mask:0xf
	v_add_f32_dpp v200, v200, v200 quad_perm:[2,3,0,1] row_mask:0xf bank_mask:0xf
	v_add_f32_dpp v199, v199, v199 quad_perm:[2,3,0,1] row_mask:0xf bank_mask:0xf
	v_add_f32_dpp v198, v198, v198 quad_perm:[2,3,0,1] row_mask:0xf bank_mask:0xf
	v_add_f32_dpp v197, v197, v197 quad_perm:[2,3,0,1] row_mask:0xf bank_mask:0xf
	v_add_f32_dpp v196, v196, v196 quad_perm:[2,3,0,1] row_mask:0xf bank_mask:0xf
	v_add_f32_dpp v195, v195, v195 quad_perm:[2,3,0,1] row_mask:0xf bank_mask:0xf
	v_add_f32_dpp v194, v194, v194 quad_perm:[2,3,0,1] row_mask:0xf bank_mask:0xf
	v_add_f32_dpp v201, v201, v201 row_half_mirror row_mask:0xf bank_mask:0xf
	v_add_f32_dpp v200, v200, v200 row_half_mirror row_mask:0xf bank_mask:0xf
	v_add_f32_dpp v199, v199, v199 row_half_mirror row_mask:0xf bank_mask:0xf
	v_add_f32_dpp v198, v198, v198 row_half_mirror row_mask:0xf bank_mask:0xf
	v_add_f32_dpp v197, v197, v197 row_half_mirror row_mask:0xf bank_mask:0xf
	v_add_f32_dpp v196, v196, v196 row_half_mirror row_mask:0xf bank_mask:0xf
	v_add_f32_dpp v195, v195, v195 row_half_mirror row_mask:0xf bank_mask:0xf
	v_add_f32_dpp v194, v194, v194 row_half_mirror row_mask:0xf bank_mask:0xf
	v_lshlrev_b32_e32 v136, 2, v193
	v_cmp_eq_u32_e32 vcc, 0, v210
	v_fmamk_f32 v128, v201, 0x3a800000, v225
	v_fmamk_f32 v129, v200, 0x3a800000, v225
	v_fmamk_f32 v130, v199, 0x3a800000, v225
	v_fmamk_f32 v131, v198, 0x3a800000, v225
	v_fmamk_f32 v132, v197, 0x3a800000, v225
	v_fmamk_f32 v133, v196, 0x3a800000, v225
	v_fmamk_f32 v134, v195, 0x3a800000, v225
	v_fmamk_f32 v135, v194, 0x3a800000, v225
	v_rsq_f32_e32 v128, v128
	v_rsq_f32_e32 v129, v129
	v_rsq_f32_e32 v130, v130
	v_rsq_f32_e32 v131, v131
	v_rsq_f32_e32 v132, v132
	v_rsq_f32_e32 v133, v133
	v_rsq_f32_e32 v134, v134
	v_rsq_f32_e32 v135, v135
	s_and_saveexec_b64 s[2:3], vcc
	ds_write_b32 v136, v128 offset:55296
	ds_write_b32 v136, v129 offset:55424
	ds_write_b32 v136, v130 offset:55552
	ds_write_b32 v136, v131 offset:55680
	ds_write_b32 v136, v132 offset:55808
	ds_write_b32 v136, v133 offset:55936
	ds_write_b32 v136, v134 offset:56064
	ds_write_b32 v136, v135 offset:56192
